# ACT stores of the hand-written P8 epilogue without the nt hint (so that the following row pass may find ACT in the Infinity Cache)
# speedup vs baseline: 1.0131x; 1.0043x over previous
;     __device__ __forceinline__ void operator()(f32x4 (&acc)[2][2][4][2], const pg8::Unit& u, int wr, int wc, int fr, int fq) const {
;     ...
;         for (int ai = 0; ai < 2; ++ai) {
;             f32x4 hal[2]; hal[0] = hal[1] = (f32x4){0.f, 0.f, 0.f, 0.f};
;             if (prompt) { const int b = 2 * ai + wr;
;                 if (b >= 1) { if (fr >= 14) {
; #pragma unroll
;                         for (int n = 0; n < 2; ++n) hal[n] = *(const LAS f32x4*)(H + ((b - 1) * 2 + (fr - 14)) * 128 + cl0 + 4 * n); } }
;                 else if ((u.pm & 7) != 0) { unsigned* fl = HFLAG + (u.pm - 1) * 96 + u.pn; unsigned sp = 0;
;                     while ((unsigned)__builtin_amdgcn_readfirstlane(__hip_atomic_load(fl, __ATOMIC_RELAXED, __HIP_MEMORY_SCOPE_AGENT)) < 4u) { __builtin_amdgcn_s_sleep(2);
;                         if ((++sp & 1023u) == 0u) { if (__hip_atomic_load(tmo, __ATOMIC_RELAXED, __HIP_MEMORY_SCOPE_AGENT) != 0u) break; if (sp > (1u << 22)) { __hip_atomic_store(tmo, 1u, __ATOMIC_RELAXED, __HIP_MEMORY_SCOPE_AGENT); break; } } }
;                     if (fr >= 14) { const unsigned long long* hp = HALO + ((size_t)((u.pm - 1) * 96 + u.pn) * 2 + (fr - 14)) * 64 + (cl0 >> 1);
; #pragma unroll
;                         for (int n = 0; n < 2; ++n) { const unsigned long long a = __hip_atomic_load(hp + 2 * n, __ATOMIC_RELAXED, __HIP_MEMORY_SCOPE_AGENT), b2 = __hip_atomic_load(hp + 2 * n + 1, __ATOMIC_RELAXED, __HIP_MEMORY_SCOPE_AGENT);
;                             hal[n] = (f32x4){__uint_as_float((unsigned)a), __uint_as_float((unsigned)(a >> 32)), __uint_as_float((unsigned)b2), __uint_as_float((unsigned)(b2 >> 32))}; } } } }
; #pragma unroll
;             for (int n = 0; n < 2; ++n) {
;                 const f32x4 w0 = *(const f32x4*)(cw + ch0 + 4 * n), w1 = *(const f32x4*)(cw + DFF + ch0 + 4 * n), w2 = *(const f32x4*)(cw + 2 * DFF + ch0 + 4 * n), bb = *(const f32x4*)(cb + ch0 + 4 * n);
; #pragma unroll
;                 for (int m = 0; m < 4; ++m) { const int row = row0 + ai * 128 + m * 16; const f32x4 g = acc[ai][0][m][n], vv = acc[ai][1][m][n]; f32x4 p1, p2;
;                     if (prompt) { const f32x4 gp = (m == 0) ? hal[n] : acc[ai][0][m > 0 ? m - 1 : 0][n];
; #pragma unroll
;                         for (int j = 0; j < 4; ++j) { p1[j] = dpp_ror1(fr == 15 ? gp[j] : g[j]); p2[j] = dpp_ror2(fr >= 14 ? gp[j] : g[j]); } }
.Lf8_noflag:
	s_lshl_b32 s20, s2, 8
	v_lshl_add_u32 v224, v242, 1, s20
	v_mov_b32_e32 v225, 0
	v_lshl_add_u64 v[224:225], s[24:25], 0, v[224:225]
	v_mad_u64_u32 v[166:167], s[44:45], v176, s83, v[224:225]
	s_mov_b32 s20, 0x1e0000
	s_mov_b32 s21, 0
	global_store_dwordx4 v[166:167], v[118:121], off
	v_lshl_add_u64 v[166:167], v[166:167], 0, s[54:55]
	global_store_dwordx4 v[166:167], v[110:113], off
	v_lshl_add_u64 v[166:167], v[166:167], 0, s[54:55]
	global_store_dwordx4 v[166:167], v[98:101], off
	v_lshl_add_u64 v[166:167], v[166:167], 0, s[54:55]
	global_store_dwordx4 v[166:167], v[90:93], off
	v_lshl_add_u64 v[166:167], v[166:167], 0, s[20:21]
	v_mov_b32_e32 v146, 0
	v_mov_b32_e32 v147, 0
	v_mov_b32_e32 v148, 0
	v_mov_b32_e32 v149, 0
	v_mov_b32_e32 v150, 0
	v_mov_b32_e32 v151, 0
	v_mov_b32_e32 v152, 0
	v_mov_b32_e32 v153, 0
	s_and_saveexec_b64 s[44:45], s[46:47]
	ds_read_b128 v[146:149], v247
	ds_read_b128 v[150:153], v247 offset:16
	s_mov_b64 exec, s[44:45]
	s_waitcnt lgkmcnt(0)
	v_pk_fma_f32 v[158:159], v[206:207], v[70:71], v[214:215]
	v_pk_fma_f32 v[160:161], v[208:209], v[72:73], v[216:217]
	v_fmac_f32_dpp v158, v70, v198 row_shr:1 row_mask:0xf bank_mask:0xf
	v_fmac_f32_dpp v159, v71, v199 row_shr:1 row_mask:0xf bank_mask:0xf
	v_fmac_f32_dpp v160, v72, v200 row_shr:1 row_mask:0xf bank_mask:0xf
	v_fmac_f32_dpp v161, v73, v201 row_shr:1 row_mask:0xf bank_mask:0xf
	v_fmac_f32_dpp v158, v70, v190 row_shr:2 row_mask:0xf bank_mask:0xf
	v_fmac_f32_dpp v159, v71, v191 row_shr:2 row_mask:0xf bank_mask:0xf
	v_fmac_f32_dpp v160, v72, v192 row_shr:2 row_mask:0xf bank_mask:0xf
	v_fmac_f32_dpp v161, v73, v193 row_shr:2 row_mask:0xf bank_mask:0xf
	v_fmac_f32_dpp v158, v146, v130 row_ror:1 row_mask:0xf bank_mask:0xf
	v_fmac_f32_dpp v159, v147, v131 row_ror:1 row_mask:0xf bank_mask:0xf
	v_fmac_f32_dpp v160, v148, v132 row_ror:1 row_mask:0xf bank_mask:0xf
	v_fmac_f32_dpp v161, v149, v133 row_ror:1 row_mask:0xf bank_mask:0xf
	v_fmac_f32_dpp v158, v146, v138 row_ror:2 row_mask:0xf bank_mask:0xf
	v_fmac_f32_dpp v159, v147, v139 row_ror:2 row_mask:0xf bank_mask:0xf
	v_fmac_f32_dpp v160, v148, v140 row_ror:2 row_mask:0xf bank_mask:0xf
	v_fmac_f32_dpp v161, v149, v141 row_ror:2 row_mask:0xf bank_mask:0xf
	v_pk_mul_f32 v[162:163], v[158:159], v[158:159]
	v_pk_mul_f32 v[164:165], v[160:161], v[160:161]
	v_pk_fma_f32 v[162:163], v[162:163], v[156:157], v[154:155]
	v_pk_fma_f32 v[164:165], v[164:165], v[156:157], v[154:155]
	v_pk_mul_f32 v[162:163], v[162:163], v[158:159]
	v_pk_mul_f32 v[164:165], v[164:165], v[160:161]
	v_exp_f32_e32 v162, v162
	v_exp_f32_e32 v163, v163
	v_exp_f32_e32 v164, v164
	v_exp_f32_e32 v165, v165
	v_pk_mul_f32 v[158:159], v[158:159], v[46:47]
	v_pk_mul_f32 v[160:161], v[160:161], v[48:49]
	v_pk_add_f32 v[162:163], v[162:163], 1.0 op_sel_hi:[1,0]
	v_pk_add_f32 v[164:165], v[164:165], 1.0 op_sel_hi:[1,0]
	v_rcp_f32_e32 v162, v162
	v_rcp_f32_e32 v163, v163
	v_rcp_f32_e32 v164, v164
	v_rcp_f32_e32 v165, v165
	s_nop 0
	v_pk_mul_f32 v[158:159], v[158:159], v[162:163]
	v_pk_mul_f32 v[160:161], v[160:161], v[164:165]
	v_cvt_pk_bf16_f32 v46, v158, v159
	v_cvt_pk_bf16_f32 v47, v160, v161
	v_pk_fma_f32 v[158:159], v[210:211], v[62:63], v[218:219]
	v_pk_fma_f32 v[160:161], v[212:213], v[64:65], v[220:221]
	v_fmac_f32_dpp v158, v62, v202 row_shr:1 row_mask:0xf bank_mask:0xf
	v_fmac_f32_dpp v159, v63, v203 row_shr:1 row_mask:0xf bank_mask:0xf
	v_fmac_f32_dpp v160, v64, v204 row_shr:1 row_mask:0xf bank_mask:0xf
	v_fmac_f32_dpp v161, v65, v205 row_shr:1 row_mask:0xf bank_mask:0xf
	v_fmac_f32_dpp v158, v62, v194 row_shr:2 row_mask:0xf bank_mask:0xf
	v_fmac_f32_dpp v159, v63, v195 row_shr:2 row_mask:0xf bank_mask:0xf
	v_fmac_f32_dpp v160, v64, v196 row_shr:2 row_mask:0xf bank_mask:0xf
	v_fmac_f32_dpp v161, v65, v197 row_shr:2 row_mask:0xf bank_mask:0xf
	v_fmac_f32_dpp v158, v150, v134 row_ror:1 row_mask:0xf bank_mask:0xf
	v_fmac_f32_dpp v159, v151, v135 row_ror:1 row_mask:0xf bank_mask:0xf
	v_fmac_f32_dpp v160, v152, v136 row_ror:1 row_mask:0xf bank_mask:0xf
	v_fmac_f32_dpp v161, v153, v137 row_ror:1 row_mask:0xf bank_mask:0xf
	v_fmac_f32_dpp v158, v150, v142 row_ror:2 row_mask:0xf bank_mask:0xf
	v_fmac_f32_dpp v159, v151, v143 row_ror:2 row_mask:0xf bank_mask:0xf
	v_fmac_f32_dpp v160, v152, v144 row_ror:2 row_mask:0xf bank_mask:0xf
	v_fmac_f32_dpp v161, v153, v145 row_ror:2 row_mask:0xf bank_mask:0xf
	v_pk_mul_f32 v[162:163], v[158:159], v[158:159]
	v_pk_mul_f32 v[164:165], v[160:161], v[160:161]
	v_pk_fma_f32 v[162:163], v[162:163], v[156:157], v[154:155]
	v_pk_fma_f32 v[164:165], v[164:165], v[156:157], v[154:155]
	v_pk_mul_f32 v[162:163], v[162:163], v[158:159]
	v_pk_mul_f32 v[164:165], v[164:165], v[160:161]
	v_exp_f32_e32 v162, v162
	v_exp_f32_e32 v163, v163
	v_exp_f32_e32 v164, v164
	v_exp_f32_e32 v165, v165
	v_pk_mul_f32 v[158:159], v[158:159], v[14:15]
	v_pk_mul_f32 v[160:161], v[160:161], v[16:17]
	v_pk_add_f32 v[162:163], v[162:163], 1.0 op_sel_hi:[1,0]
	v_pk_add_f32 v[164:165], v[164:165], 1.0 op_sel_hi:[1,0]
	v_rcp_f32_e32 v162, v162
	v_rcp_f32_e32 v163, v163
	v_rcp_f32_e32 v164, v164
	v_rcp_f32_e32 v165, v165
	s_nop 0
	v_pk_mul_f32 v[158:159], v[158:159], v[162:163]
	v_pk_mul_f32 v[160:161], v[160:161], v[164:165]
	v_cvt_pk_bf16_f32 v48, v158, v159
	v_cvt_pk_bf16_f32 v49, v160, v161
	global_store_dwordx4 v[166:167], v[46:49], off
	v_lshl_add_u64 v[166:167], v[166:167], 0, s[54:55]
	v_pk_fma_f32 v[158:159], v[206:207], v[38:39], v[214:215]
	v_pk_fma_f32 v[160:161], v[208:209], v[40:41], v[216:217]
	v_fmac_f32_dpp v158, v38, v198 row_shr:1 row_mask:0xf bank_mask:0xf
	v_fmac_f32_dpp v159, v39, v199 row_shr:1 row_mask:0xf bank_mask:0xf
; __device__ __forceinline__ unsigned cvt_pk_bf16(float lo, float hi) { unsigned r; asm("v_cvt_pk_bf16_f32 %0, %1, %2" : "=v"(r) : "v"(lo), "v"(hi)); return r; }
; __device__ __forceinline__ float gelu_tanh(float x) { const float u = 0.7978845608028654f * (x + 0.044715f * x * x * x); return x * sigmoidf_(2.0f * u); }
; __device__ __forceinline__ float dpp_ror1(float v) { return __builtin_bit_cast(float, __builtin_amdgcn_update_dpp(0, __builtin_bit_cast(int, v), 0x121, 0xf, 0xf, false)); }
; __device__ __forceinline__ float dpp_ror2(float v) { return __builtin_bit_cast(float, __builtin_amdgcn_update_dpp(0, __builtin_bit_cast(int, v), 0x122, 0xf, 0xf, false)); }
;     __device__ __forceinline__ void operator()(f32x4 (&acc)[2][2][4][2], const pg8::Unit& u, int wr, int wc, int fr, int fq) const {
;     ...
;             for (int n = 0; n < 2; ++n) {
;                 const f32x4 w0 = *(const f32x4*)(cw + ch0 + 4 * n), w1 = *(const f32x4*)(cw + DFF + ch0 + 4 * n), w2 = *(const f32x4*)(cw + 2 * DFF + ch0 + 4 * n), bb = *(const f32x4*)(cb + ch0 + 4 * n);
; #pragma unroll
;                 for (int m = 0; m < 4; ++m) { const int row = row0 + ai * 128 + m * 16; const f32x4 g = acc[ai][0][m][n], vv = acc[ai][1][m][n]; f32x4 p1, p2;
;                     if (prompt) { const f32x4 gp = (m == 0) ? hal[n] : acc[ai][0][m > 0 ? m - 1 : 0][n];
; #pragma unroll
;                         for (int j = 0; j < 4; ++j) { p1[j] = dpp_ror1(fr == 15 ? gp[j] : g[j]); p2[j] = dpp_ror2(fr >= 14 ? gp[j] : g[j]); } }
;                     else { const int t = fr & 3; const float* sp = stf + (size_t)((row - MP) >> 2) * 2 * DFF + ch0 + 4 * n;
;                         f32x4 b0 = (f32x4){0.f, 0.f, 0.f, 0.f}, b1 = b0; if (t == 0) b0 = *(const f32x4*)sp; if (t <= 1) b1 = *(const f32x4*)(sp + DFF);
; #pragma unroll
;                         for (int j = 0; j < 4; ++j) { const float r1 = dpp_ror1(g[j]), r2 = dpp_ror2(g[j]); p1[j] = t >= 1 ? r1 : b1[j]; p2[j] = t >= 2 ? r2 : (t == 1 ? b1[j] : b0[j]); } }
;                     float o[4];
; #pragma unroll
;                     for (int j = 0; j < 4; ++j) { const float y = bb[j] + w0[j] * p2[j] + w1[j] * p1[j] + w2[j] * g[j]; o[j] = gelu_tanh(y) * vv[j]; }
;                     u32x2 w; w.x = cvt_pk_bf16(o[0], o[1]); w.y = cvt_pk_bf16(o[2], o[3]);
;                     *(u32x2*)(ACT + (size_t)row * DFF + ch0 + 4 * n) = w; } } }
	v_fmac_f32_dpp v160, v40, v200 row_shr:1 row_mask:0xf bank_mask:0xf
	v_fmac_f32_dpp v161, v41, v201 row_shr:1 row_mask:0xf bank_mask:0xf
	v_fmac_f32_dpp v158, v38, v190 row_shr:2 row_mask:0xf bank_mask:0xf
	v_fmac_f32_dpp v159, v39, v191 row_shr:2 row_mask:0xf bank_mask:0xf
	v_fmac_f32_dpp v160, v40, v192 row_shr:2 row_mask:0xf bank_mask:0xf
	v_fmac_f32_dpp v161, v41, v193 row_shr:2 row_mask:0xf bank_mask:0xf
	v_fmac_f32_dpp v158, v70, v130 row_ror:1 row_mask:0xf bank_mask:0xf
	v_fmac_f32_dpp v159, v71, v131 row_ror:1 row_mask:0xf bank_mask:0xf
	v_fmac_f32_dpp v160, v72, v132 row_ror:1 row_mask:0xf bank_mask:0xf
	v_fmac_f32_dpp v161, v73, v133 row_ror:1 row_mask:0xf bank_mask:0xf
	v_fmac_f32_dpp v158, v70, v138 row_ror:2 row_mask:0xf bank_mask:0xf
	v_fmac_f32_dpp v159, v71, v139 row_ror:2 row_mask:0xf bank_mask:0xf
	v_fmac_f32_dpp v160, v72, v140 row_ror:2 row_mask:0xf bank_mask:0xf
	v_fmac_f32_dpp v161, v73, v141 row_ror:2 row_mask:0xf bank_mask:0xf
	v_pk_mul_f32 v[162:163], v[158:159], v[158:159]
	v_pk_mul_f32 v[164:165], v[160:161], v[160:161]
	v_pk_fma_f32 v[162:163], v[162:163], v[156:157], v[154:155]
	v_pk_fma_f32 v[164:165], v[164:165], v[156:157], v[154:155]
	v_pk_mul_f32 v[162:163], v[162:163], v[158:159]
	v_pk_mul_f32 v[164:165], v[164:165], v[160:161]
	v_exp_f32_e32 v162, v162
	v_exp_f32_e32 v163, v163
	v_exp_f32_e32 v164, v164
	v_exp_f32_e32 v165, v165
	v_pk_mul_f32 v[158:159], v[158:159], v[42:43]
	v_pk_mul_f32 v[160:161], v[160:161], v[44:45]
	v_pk_add_f32 v[162:163], v[162:163], 1.0 op_sel_hi:[1,0]
	v_pk_add_f32 v[164:165], v[164:165], 1.0 op_sel_hi:[1,0]
	v_rcp_f32_e32 v162, v162
	v_rcp_f32_e32 v163, v163
	v_rcp_f32_e32 v164, v164
	v_rcp_f32_e32 v165, v165
	s_nop 0
	v_pk_mul_f32 v[158:159], v[158:159], v[162:163]
	v_pk_mul_f32 v[160:161], v[160:161], v[164:165]
	v_cvt_pk_bf16_f32 v42, v158, v159
	v_cvt_pk_bf16_f32 v43, v160, v161
	v_pk_fma_f32 v[158:159], v[210:211], v[54:55], v[218:219]
	v_pk_fma_f32 v[160:161], v[212:213], v[56:57], v[220:221]
	v_fmac_f32_dpp v158, v54, v202 row_shr:1 row_mask:0xf bank_mask:0xf
	v_fmac_f32_dpp v159, v55, v203 row_shr:1 row_mask:0xf bank_mask:0xf
	v_fmac_f32_dpp v160, v56, v204 row_shr:1 row_mask:0xf bank_mask:0xf
	v_fmac_f32_dpp v161, v57, v205 row_shr:1 row_mask:0xf bank_mask:0xf
	v_fmac_f32_dpp v158, v54, v194 row_shr:2 row_mask:0xf bank_mask:0xf
	v_fmac_f32_dpp v159, v55, v195 row_shr:2 row_mask:0xf bank_mask:0xf
	v_fmac_f32_dpp v160, v56, v196 row_shr:2 row_mask:0xf bank_mask:0xf
	v_fmac_f32_dpp v161, v57, v197 row_shr:2 row_mask:0xf bank_mask:0xf
	v_fmac_f32_dpp v158, v62, v134 row_ror:1 row_mask:0xf bank_mask:0xf
	v_fmac_f32_dpp v159, v63, v135 row_ror:1 row_mask:0xf bank_mask:0xf
	v_fmac_f32_dpp v160, v64, v136 row_ror:1 row_mask:0xf bank_mask:0xf
	v_fmac_f32_dpp v161, v65, v137 row_ror:1 row_mask:0xf bank_mask:0xf
	v_fmac_f32_dpp v158, v62, v142 row_ror:2 row_mask:0xf bank_mask:0xf
	v_fmac_f32_dpp v159, v63, v143 row_ror:2 row_mask:0xf bank_mask:0xf
	v_fmac_f32_dpp v160, v64, v144 row_ror:2 row_mask:0xf bank_mask:0xf
	v_fmac_f32_dpp v161, v65, v145 row_ror:2 row_mask:0xf bank_mask:0xf
	v_pk_mul_f32 v[162:163], v[158:159], v[158:159]
	v_pk_mul_f32 v[164:165], v[160:161], v[160:161]
	v_pk_fma_f32 v[162:163], v[162:163], v[156:157], v[154:155]
	v_pk_fma_f32 v[164:165], v[164:165], v[156:157], v[154:155]
	v_pk_mul_f32 v[162:163], v[162:163], v[158:159]
	v_pk_mul_f32 v[164:165], v[164:165], v[160:161]
	v_exp_f32_e32 v162, v162
	v_exp_f32_e32 v163, v163
	v_exp_f32_e32 v164, v164
	v_exp_f32_e32 v165, v165
	v_pk_mul_f32 v[158:159], v[158:159], v[10:11]
	v_pk_mul_f32 v[160:161], v[160:161], v[12:13]
	v_pk_add_f32 v[162:163], v[162:163], 1.0 op_sel_hi:[1,0]
	v_pk_add_f32 v[164:165], v[164:165], 1.0 op_sel_hi:[1,0]
	v_rcp_f32_e32 v162, v162
	v_rcp_f32_e32 v163, v163
	v_rcp_f32_e32 v164, v164
	v_rcp_f32_e32 v165, v165
	s_nop 0
	v_pk_mul_f32 v[158:159], v[158:159], v[162:163]
	v_pk_mul_f32 v[160:161], v[160:161], v[164:165]
	v_cvt_pk_bf16_f32 v44, v158, v159
	v_cvt_pk_bf16_f32 v45, v160, v161
	global_store_dwordx4 v[166:167], v[42:45], off
	v_lshl_add_u64 v[166:167], v[166:167], 0, s[54:55]
	v_pk_fma_f32 v[158:159], v[206:207], v[30:31], v[214:215]
	v_pk_fma_f32 v[160:161], v[208:209], v[32:33], v[216:217]
	v_fmac_f32_dpp v158, v30, v198 row_shr:1 row_mask:0xf bank_mask:0xf
	v_fmac_f32_dpp v159, v31, v199 row_shr:1 row_mask:0xf bank_mask:0xf
	v_fmac_f32_dpp v160, v32, v200 row_shr:1 row_mask:0xf bank_mask:0xf
	v_fmac_f32_dpp v161, v33, v201 row_shr:1 row_mask:0xf bank_mask:0xf
	v_fmac_f32_dpp v158, v30, v190 row_shr:2 row_mask:0xf bank_mask:0xf
	v_fmac_f32_dpp v159, v31, v191 row_shr:2 row_mask:0xf bank_mask:0xf
	v_fmac_f32_dpp v160, v32, v192 row_shr:2 row_mask:0xf bank_mask:0xf
	v_fmac_f32_dpp v161, v33, v193 row_shr:2 row_mask:0xf bank_mask:0xf
	v_fmac_f32_dpp v158, v38, v130 row_ror:1 row_mask:0xf bank_mask:0xf
	v_fmac_f32_dpp v159, v39, v131 row_ror:1 row_mask:0xf bank_mask:0xf
	v_fmac_f32_dpp v160, v40, v132 row_ror:1 row_mask:0xf bank_mask:0xf
	v_fmac_f32_dpp v161, v41, v133 row_ror:1 row_mask:0xf bank_mask:0xf
	v_fmac_f32_dpp v158, v38, v138 row_ror:2 row_mask:0xf bank_mask:0xf
	v_fmac_f32_dpp v159, v39, v139 row_ror:2 row_mask:0xf bank_mask:0xf
	v_fmac_f32_dpp v160, v40, v140 row_ror:2 row_mask:0xf bank_mask:0xf
	v_fmac_f32_dpp v161, v41, v141 row_ror:2 row_mask:0xf bank_mask:0xf
	v_pk_mul_f32 v[162:163], v[158:159], v[158:159]
	v_pk_mul_f32 v[164:165], v[160:161], v[160:161]
	v_pk_fma_f32 v[162:163], v[162:163], v[156:157], v[154:155]
	v_pk_fma_f32 v[164:165], v[164:165], v[156:157], v[154:155]
	v_pk_mul_f32 v[162:163], v[162:163], v[158:159]
	v_pk_mul_f32 v[164:165], v[164:165], v[160:161]
; __device__ __forceinline__ unsigned cvt_pk_bf16(float lo, float hi) { unsigned r; asm("v_cvt_pk_bf16_f32 %0, %1, %2" : "=v"(r) : "v"(lo), "v"(hi)); return r; }
; __device__ __forceinline__ float gelu_tanh(float x) { const float u = 0.7978845608028654f * (x + 0.044715f * x * x * x); return x * sigmoidf_(2.0f * u); }
; __device__ __forceinline__ float dpp_ror1(float v) { return __builtin_bit_cast(float, __builtin_amdgcn_update_dpp(0, __builtin_bit_cast(int, v), 0x121, 0xf, 0xf, false)); }
; __device__ __forceinline__ float dpp_ror2(float v) { return __builtin_bit_cast(float, __builtin_amdgcn_update_dpp(0, __builtin_bit_cast(int, v), 0x122, 0xf, 0xf, false)); }
;     __device__ __forceinline__ void operator()(f32x4 (&acc)[2][2][4][2], const pg8::Unit& u, int wr, int wc, int fr, int fq) const {
;     ...
;             for (int n = 0; n < 2; ++n) {
;                 const f32x4 w0 = *(const f32x4*)(cw + ch0 + 4 * n), w1 = *(const f32x4*)(cw + DFF + ch0 + 4 * n), w2 = *(const f32x4*)(cw + 2 * DFF + ch0 + 4 * n), bb = *(const f32x4*)(cb + ch0 + 4 * n);
; #pragma unroll
;                 for (int m = 0; m < 4; ++m) { const int row = row0 + ai * 128 + m * 16; const f32x4 g = acc[ai][0][m][n], vv = acc[ai][1][m][n]; f32x4 p1, p2;
;                     if (prompt) { const f32x4 gp = (m == 0) ? hal[n] : acc[ai][0][m > 0 ? m - 1 : 0][n];
; #pragma unroll
;                         for (int j = 0; j < 4; ++j) { p1[j] = dpp_ror1(fr == 15 ? gp[j] : g[j]); p2[j] = dpp_ror2(fr >= 14 ? gp[j] : g[j]); } }
;                     else { const int t = fr & 3; const float* sp = stf + (size_t)((row - MP) >> 2) * 2 * DFF + ch0 + 4 * n;
;                         f32x4 b0 = (f32x4){0.f, 0.f, 0.f, 0.f}, b1 = b0; if (t == 0) b0 = *(const f32x4*)sp; if (t <= 1) b1 = *(const f32x4*)(sp + DFF);
; #pragma unroll
;                         for (int j = 0; j < 4; ++j) { const float r1 = dpp_ror1(g[j]), r2 = dpp_ror2(g[j]); p1[j] = t >= 1 ? r1 : b1[j]; p2[j] = t >= 2 ? r2 : (t == 1 ? b1[j] : b0[j]); } }
;                     float o[4];
; #pragma unroll
;                     for (int j = 0; j < 4; ++j) { const float y = bb[j] + w0[j] * p2[j] + w1[j] * p1[j] + w2[j] * g[j]; o[j] = gelu_tanh(y) * vv[j]; }
;                     u32x2 w; w.x = cvt_pk_bf16(o[0], o[1]); w.y = cvt_pk_bf16(o[2], o[3]);
;                     *(u32x2*)(ACT + (size_t)row * DFF + ch0 + 4 * n) = w; } } }
	v_exp_f32_e32 v162, v162
	v_exp_f32_e32 v163, v163
	v_exp_f32_e32 v164, v164
	v_exp_f32_e32 v165, v165
	v_pk_mul_f32 v[158:159], v[158:159], v[34:35]
	v_pk_mul_f32 v[160:161], v[160:161], v[36:37]
	v_pk_add_f32 v[162:163], v[162:163], 1.0 op_sel_hi:[1,0]
	v_pk_add_f32 v[164:165], v[164:165], 1.0 op_sel_hi:[1,0]
	v_rcp_f32_e32 v162, v162
	v_rcp_f32_e32 v163, v163
	v_rcp_f32_e32 v164, v164
	v_rcp_f32_e32 v165, v165
	s_nop 0
	v_pk_mul_f32 v[158:159], v[158:159], v[162:163]
	v_pk_mul_f32 v[160:161], v[160:161], v[164:165]
	v_cvt_pk_bf16_f32 v34, v158, v159
	v_cvt_pk_bf16_f32 v35, v160, v161
	v_pk_fma_f32 v[158:159], v[210:211], v[50:51], v[218:219]
	v_pk_fma_f32 v[160:161], v[212:213], v[52:53], v[220:221]
	v_fmac_f32_dpp v158, v50, v202 row_shr:1 row_mask:0xf bank_mask:0xf
	v_fmac_f32_dpp v159, v51, v203 row_shr:1 row_mask:0xf bank_mask:0xf
	v_fmac_f32_dpp v160, v52, v204 row_shr:1 row_mask:0xf bank_mask:0xf
	v_fmac_f32_dpp v161, v53, v205 row_shr:1 row_mask:0xf bank_mask:0xf
	v_fmac_f32_dpp v158, v50, v194 row_shr:2 row_mask:0xf bank_mask:0xf
	v_fmac_f32_dpp v159, v51, v195 row_shr:2 row_mask:0xf bank_mask:0xf
	v_fmac_f32_dpp v160, v52, v196 row_shr:2 row_mask:0xf bank_mask:0xf
	v_fmac_f32_dpp v161, v53, v197 row_shr:2 row_mask:0xf bank_mask:0xf
	v_fmac_f32_dpp v158, v54, v134 row_ror:1 row_mask:0xf bank_mask:0xf
	v_fmac_f32_dpp v159, v55, v135 row_ror:1 row_mask:0xf bank_mask:0xf
	v_fmac_f32_dpp v160, v56, v136 row_ror:1 row_mask:0xf bank_mask:0xf
	v_fmac_f32_dpp v161, v57, v137 row_ror:1 row_mask:0xf bank_mask:0xf
	v_fmac_f32_dpp v158, v54, v142 row_ror:2 row_mask:0xf bank_mask:0xf
	v_fmac_f32_dpp v159, v55, v143 row_ror:2 row_mask:0xf bank_mask:0xf
	v_fmac_f32_dpp v160, v56, v144 row_ror:2 row_mask:0xf bank_mask:0xf
	v_fmac_f32_dpp v161, v57, v145 row_ror:2 row_mask:0xf bank_mask:0xf
	v_pk_mul_f32 v[162:163], v[158:159], v[158:159]
	v_pk_mul_f32 v[164:165], v[160:161], v[160:161]
	v_pk_fma_f32 v[162:163], v[162:163], v[156:157], v[154:155]
	v_pk_fma_f32 v[164:165], v[164:165], v[156:157], v[154:155]
	v_pk_mul_f32 v[162:163], v[162:163], v[158:159]
	v_pk_mul_f32 v[164:165], v[164:165], v[160:161]
	v_exp_f32_e32 v162, v162
	v_exp_f32_e32 v163, v163
	v_exp_f32_e32 v164, v164
	v_exp_f32_e32 v165, v165
	v_pk_mul_f32 v[158:159], v[158:159], v[6:7]
	v_pk_mul_f32 v[160:161], v[160:161], v[8:9]
	v_pk_add_f32 v[162:163], v[162:163], 1.0 op_sel_hi:[1,0]
	v_pk_add_f32 v[164:165], v[164:165], 1.0 op_sel_hi:[1,0]
	v_rcp_f32_e32 v162, v162
	v_rcp_f32_e32 v163, v163
	v_rcp_f32_e32 v164, v164
	v_rcp_f32_e32 v165, v165
	s_nop 0
	v_pk_mul_f32 v[158:159], v[158:159], v[162:163]
	v_pk_mul_f32 v[160:161], v[160:161], v[164:165]
	v_cvt_pk_bf16_f32 v36, v158, v159
	v_cvt_pk_bf16_f32 v37, v160, v161
	global_store_dwordx4 v[166:167], v[34:37], off
	v_lshl_add_u64 v[166:167], v[166:167], 0, s[54:55]
	v_pk_fma_f32 v[158:159], v[206:207], v[26:27], v[214:215]
	v_pk_fma_f32 v[160:161], v[208:209], v[28:29], v[216:217]
	v_fmac_f32_dpp v158, v26, v198 row_shr:1 row_mask:0xf bank_mask:0xf
	v_fmac_f32_dpp v159, v27, v199 row_shr:1 row_mask:0xf bank_mask:0xf
	v_fmac_f32_dpp v160, v28, v200 row_shr:1 row_mask:0xf bank_mask:0xf
	v_fmac_f32_dpp v161, v29, v201 row_shr:1 row_mask:0xf bank_mask:0xf
	v_fmac_f32_dpp v158, v26, v190 row_shr:2 row_mask:0xf bank_mask:0xf
	v_fmac_f32_dpp v159, v27, v191 row_shr:2 row_mask:0xf bank_mask:0xf
	v_fmac_f32_dpp v160, v28, v192 row_shr:2 row_mask:0xf bank_mask:0xf
	v_fmac_f32_dpp v161, v29, v193 row_shr:2 row_mask:0xf bank_mask:0xf
	v_fmac_f32_dpp v158, v30, v130 row_ror:1 row_mask:0xf bank_mask:0xf
	v_fmac_f32_dpp v159, v31, v131 row_ror:1 row_mask:0xf bank_mask:0xf
	v_fmac_f32_dpp v160, v32, v132 row_ror:1 row_mask:0xf bank_mask:0xf
; template <class Epi, class Geom, class Sched, bool ALIGN_EPI, bool I8 = false>
; __device__ __forceinline__ void gemm_phase(LAS unsigned char* lds, const Gemm g, const Sched& S, const Epi& E) {
;     ...
;         if constexpr (ALIGN_EPI) { if (wr == 0) PG8_BAR; }
;         E(acc, cur, wr, wc, fr, fq);
;         if (!has_next) break;
; #pragma unroll
;         for (int a = 0; a < 2; ++a)
; #pragma unroll
;             for (int b = 0; b < 2; ++b)
; #pragma unroll
;                 for (int m = 0; m < 4; ++m)
; #pragma unroll
;                     for (int n = 0; n < 2; ++n) acc[a][b][m][n] = (f32x4){0.f, 0.f, 0.f, 0.f};
;         cur = nxt; cA = nA; cB = nB; ++ui;
;     __device__ __forceinline__ void operator()(f32x4 (&acc)[2][2][4][2], const pg8::Unit& u, int wr, int wc, int fr, int fq) const {
;     ...
;             for (int n = 0; n < 2; ++n) {
;                 const f32x4 w0 = *(const f32x4*)(cw + ch0 + 4 * n), w1 = *(const f32x4*)(cw + DFF + ch0 + 4 * n), w2 = *(const f32x4*)(cw + 2 * DFF + ch0 + 4 * n), bb = *(const f32x4*)(cb + ch0 + 4 * n);
; #pragma unroll
;                 for (int m = 0; m < 4; ++m) { const int row = row0 + ai * 128 + m * 16; const f32x4 g = acc[ai][0][m][n], vv = acc[ai][1][m][n]; f32x4 p1, p2;
;                     if (prompt) { const f32x4 gp = (m == 0) ? hal[n] : acc[ai][0][m > 0 ? m - 1 : 0][n];
; #pragma unroll
;                         for (int j = 0; j < 4; ++j) { p1[j] = dpp_ror1(fr == 15 ? gp[j] : g[j]); p2[j] = dpp_ror2(fr >= 14 ? gp[j] : g[j]); } }
;                     else { const int t = fr & 3; const float* sp = stf + (size_t)((row - MP) >> 2) * 2 * DFF + ch0 + 4 * n;
;                         f32x4 b0 = (f32x4){0.f, 0.f, 0.f, 0.f}, b1 = b0; if (t == 0) b0 = *(const f32x4*)sp; if (t <= 1) b1 = *(const f32x4*)(sp + DFF);
; #pragma unroll
;                         for (int j = 0; j < 4; ++j) { const float r1 = dpp_ror1(g[j]), r2 = dpp_ror2(g[j]); p1[j] = t >= 1 ? r1 : b1[j]; p2[j] = t >= 2 ? r2 : (t == 1 ? b1[j] : b0[j]); } }
;                     float o[4];
; #pragma unroll
;                     for (int j = 0; j < 4; ++j) { const float y = bb[j] + w0[j] * p2[j] + w1[j] * p1[j] + w2[j] * g[j]; o[j] = gelu_tanh(y) * vv[j]; }
;                     u32x2 w; w.x = cvt_pk_bf16(o[0], o[1]); w.y = cvt_pk_bf16(o[2], o[3]);
;                     *(u32x2*)(ACT + (size_t)row * DFF + ch0 + 4 * n) = w; } } }
	v_fmac_f32_dpp v161, v33, v133 row_ror:1 row_mask:0xf bank_mask:0xf
	v_fmac_f32_dpp v158, v30, v138 row_ror:2 row_mask:0xf bank_mask:0xf
	v_fmac_f32_dpp v159, v31, v139 row_ror:2 row_mask:0xf bank_mask:0xf
	v_fmac_f32_dpp v160, v32, v140 row_ror:2 row_mask:0xf bank_mask:0xf
	v_fmac_f32_dpp v161, v33, v141 row_ror:2 row_mask:0xf bank_mask:0xf
	v_pk_mul_f32 v[162:163], v[158:159], v[158:159]
	v_pk_mul_f32 v[164:165], v[160:161], v[160:161]
	v_pk_fma_f32 v[162:163], v[162:163], v[156:157], v[154:155]
	v_pk_fma_f32 v[164:165], v[164:165], v[156:157], v[154:155]
	v_pk_mul_f32 v[162:163], v[162:163], v[158:159]
	v_pk_mul_f32 v[164:165], v[164:165], v[160:161]
	v_exp_f32_e32 v162, v162
	v_exp_f32_e32 v163, v163
	v_exp_f32_e32 v164, v164
	v_exp_f32_e32 v165, v165
	v_pk_mul_f32 v[158:159], v[158:159], v[22:23]
	v_pk_mul_f32 v[160:161], v[160:161], v[24:25]
	v_pk_add_f32 v[162:163], v[162:163], 1.0 op_sel_hi:[1,0]
	v_pk_add_f32 v[164:165], v[164:165], 1.0 op_sel_hi:[1,0]
	v_rcp_f32_e32 v162, v162
	v_rcp_f32_e32 v163, v163
	v_rcp_f32_e32 v164, v164
	v_rcp_f32_e32 v165, v165
	s_nop 0
	v_pk_mul_f32 v[158:159], v[158:159], v[162:163]
	v_pk_mul_f32 v[160:161], v[160:161], v[164:165]
	v_cvt_pk_bf16_f32 v22, v158, v159
	v_cvt_pk_bf16_f32 v23, v160, v161
	v_pk_fma_f32 v[158:159], v[210:211], v[18:19], v[218:219]
	v_pk_fma_f32 v[160:161], v[212:213], v[20:21], v[220:221]
	v_fmac_f32_dpp v158, v18, v202 row_shr:1 row_mask:0xf bank_mask:0xf
	v_fmac_f32_dpp v159, v19, v203 row_shr:1 row_mask:0xf bank_mask:0xf
	v_fmac_f32_dpp v160, v20, v204 row_shr:1 row_mask:0xf bank_mask:0xf
	v_fmac_f32_dpp v161, v21, v205 row_shr:1 row_mask:0xf bank_mask:0xf
	v_fmac_f32_dpp v158, v18, v194 row_shr:2 row_mask:0xf bank_mask:0xf
	v_fmac_f32_dpp v159, v19, v195 row_shr:2 row_mask:0xf bank_mask:0xf
	v_fmac_f32_dpp v160, v20, v196 row_shr:2 row_mask:0xf bank_mask:0xf
	v_fmac_f32_dpp v161, v21, v197 row_shr:2 row_mask:0xf bank_mask:0xf
	v_fmac_f32_dpp v158, v50, v134 row_ror:1 row_mask:0xf bank_mask:0xf
	v_fmac_f32_dpp v159, v51, v135 row_ror:1 row_mask:0xf bank_mask:0xf
	v_fmac_f32_dpp v160, v52, v136 row_ror:1 row_mask:0xf bank_mask:0xf
	v_fmac_f32_dpp v161, v53, v137 row_ror:1 row_mask:0xf bank_mask:0xf
	v_fmac_f32_dpp v158, v50, v142 row_ror:2 row_mask:0xf bank_mask:0xf
	v_fmac_f32_dpp v159, v51, v143 row_ror:2 row_mask:0xf bank_mask:0xf
	v_fmac_f32_dpp v160, v52, v144 row_ror:2 row_mask:0xf bank_mask:0xf
	v_fmac_f32_dpp v161, v53, v145 row_ror:2 row_mask:0xf bank_mask:0xf
	v_pk_mul_f32 v[162:163], v[158:159], v[158:159]
	v_pk_mul_f32 v[164:165], v[160:161], v[160:161]
	v_pk_fma_f32 v[162:163], v[162:163], v[156:157], v[154:155]
	v_pk_fma_f32 v[164:165], v[164:165], v[156:157], v[154:155]
	v_pk_mul_f32 v[162:163], v[162:163], v[158:159]
	v_pk_mul_f32 v[164:165], v[164:165], v[160:161]
	v_exp_f32_e32 v162, v162
	v_exp_f32_e32 v163, v163
	v_exp_f32_e32 v164, v164
	v_exp_f32_e32 v165, v165
	v_pk_mul_f32 v[158:159], v[158:159], v[2:3]
	v_pk_mul_f32 v[160:161], v[160:161], v[4:5]
	v_pk_add_f32 v[162:163], v[162:163], 1.0 op_sel_hi:[1,0]
	v_pk_add_f32 v[164:165], v[164:165], 1.0 op_sel_hi:[1,0]
	v_rcp_f32_e32 v162, v162
	v_rcp_f32_e32 v163, v163
	v_rcp_f32_e32 v164, v164
	v_rcp_f32_e32 v165, v165
	s_nop 0
	v_pk_mul_f32 v[158:159], v[158:159], v[162:163]
	v_pk_mul_f32 v[160:161], v[160:161], v[164:165]
	v_cvt_pk_bf16_f32 v24, v158, v159
	v_cvt_pk_bf16_f32 v25, v160, v161
	global_store_dwordx4 v[166:167], v[22:25], off
	s_andn2_b64 vcc, exec, s[18:19]
	s_mov_b64 s[2:3], -1
	s_cbranch_vccnz .LBB0_2516
	v_readlane_b32 s2, v255, 19
	v_readlane_b32 s3, v255, 20
	s_nop 0
	s_andn2_b64 vcc, exec, s[2:3]
	s_cbranch_vccnz .LBB0_2515
	s_barrier
	s_branch .LBB0_2515
